# v3 + panel exchange by direct polling of the published partials (slots zeroed in phase 0; no drain / arrival counter / counter poll / flag barrier) in all 4 exchange epilogues
# baseline (speedup 1.0000x reference)
; #define LAS __attribute__((address_space(3)))
; #define P0STAMP(i) do { if (PROBE_K >= 200 && F.bid == 0 && F.tid == 0) ((unsigned long long*)(F.ws + WS_CTL))[25600 + 96 + (i)] = __builtin_amdgcn_s_memrealtime(); } while (0)
; template <int PART> __device__ __forceinline__ void phase_convert(Frame& F) {
;     LAS float* scr = (LAS float*)(F.lds + F.wave * 16640);
;     const int NGW = F.G * NWAVES, gw = (F.bid * NWAVES + F.wave + (PART == 1 ? NGW / 2 : 0)) % NGW;
;     constexpr int I_GLU = (D / 64) * (2 * D / 64), I_IN = (D / 64) * (NQKVR / 64), I_OUT = (D / 64) * (D / 64), I_1 = (D / 64) * (DFF / 64), I_2 = (DFF / 64) * (D / 64);
;     constexpr int NITEMS = PART == 0 ? I_IN + I_OUT + I_1 + I_2 : I_GLU + I_1 + I_2;
;     bf16_t* WGLU = (bf16_t*)(F.ws + WS_WGLU); bf16_t* WIN = (bf16_t*)(F.ws + WS_WIN); bf16_t* WOUT = (bf16_t*)(F.ws + WS_WOUT);
;     bf16_t* W1 = (bf16_t*)(F.ws + WS_W1); bf16_t* W2 = (bf16_t*)(F.ws + WS_W2);
;     constexpr int l = PART == 0 ? 1 : 0;
;     for (int it = gw; it < NITEMS; it += NGW) {
; template <int PHX> __device__ __forceinline__ void run_phase(Frame& F) {
;     ...
;     if constexpr (PH == 0) { const bool odd = F.bid & 1;
;         P0STAMP(0); if (odd) phase_convert<0>(F); TabRegs TR; tables_issue(F, TR); ModRegs MR; mod_issue(F, MR); phase_s5tables(F, TR); P0STAMP(1); mod_finish(F, MR); P0STAMP(2); if (!odd) phase_convert<0>(F); P0STAMP(3);
.LBB0_5:
	s_or_b64 exec, exec, s[6:7]
	s_load_dwordx2 s[92:93], s[0:1], 0xc8
	s_load_dwordx16 s[8:23], s[0:1], 0x80
	s_lshr_b32 s3, s90, 6
	s_waitcnt lgkmcnt(0)
	v_lshl_add_u32 v1, s2, 9, v0
	v_lshlrev_b32_e32 v2, 4, v1
	v_mov_b32_e32 v4, 0
	v_mov_b32_e32 v5, 0
	v_mov_b32_e32 v6, 0
	v_mov_b32_e32 v7, 0
	v_add_u32_e32 v3, 0x200000, v2
	v_cmp_gt_u32_e32 vcc, 0xc000, v1
	s_and_saveexec_b64 s[6:7], vcc
	global_store_dwordx4 v3, v[4:7], s[34:35]
	s_mov_b64 exec, s[6:7]
	v_add_u32_e32 v3, 0x380000, v2
	v_cmp_gt_u32_e32 vcc, 0x8000, v1
	s_and_saveexec_b64 s[6:7], vcc
	global_store_dwordx4 v3, v[4:7], s[34:35]
	s_mov_b64 exec, s[6:7]
	s_and_b32 s4, s92, 1
	v_writelane_b32 v252, s8, 18
	s_cmp_eq_u64 s[4:5], 0
	s_nop 0
	v_writelane_b32 v252, s9, 19
	v_writelane_b32 v252, s10, 20
	v_writelane_b32 v252, s11, 21
	v_writelane_b32 v252, s12, 22
	v_writelane_b32 v252, s13, 23
	v_writelane_b32 v252, s14, 24
	v_writelane_b32 v252, s15, 25
	v_writelane_b32 v252, s16, 26
	v_writelane_b32 v252, s17, 27
	v_writelane_b32 v252, s18, 28
	v_writelane_b32 v252, s19, 29
	v_writelane_b32 v252, s20, 30
	v_writelane_b32 v252, s21, 31
	v_writelane_b32 v252, s22, 32
	v_writelane_b32 v252, s23, 33
	s_cbranch_scc1 .LBB0_280
	s_bitcmp0_b32 s2, 0
	v_mbcnt_lo_u32_b32 v0, -1, 0
	s_cselect_b64 s[12:13], -1, 0
	s_mov_b32 s1, 0
	v_mbcnt_hi_u32_b32 v120, -1, v0
	s_and_b64 vcc, exec, s[12:13]
	s_cbranch_vccnz .LBB0_31
	s_lshl_b32 s0, s33, 3
	s_abs_i32 s5, s0
	v_cvt_f32_u32_e32 v0, s5
	s_sub_i32 s7, 0, s5
	s_lshl_b32 s4, s2, 3
	s_add_i32 s6, s4, s3
	v_rcp_iflag_f32_e32 v0, v0
	s_ashr_i32 s4, s6, 31
	s_abs_i32 s6, s6
	v_mul_f32_e32 v0, 0x4f7ffffe, v0
	v_cvt_u32_f32_e32 v0, v0
	s_nop 0
	v_readfirstlane_b32 s8, v0
	s_mul_i32 s7, s7, s8
	s_mul_hi_u32 s7, s8, s7
	s_add_i32 s8, s8, s7
	s_mul_hi_u32 s7, s6, s8
	s_mul_i32 s7, s7, s5
	s_sub_i32 s6, s6, s7
	s_sub_i32 s7, s6, s5
	s_cmp_ge_u32 s6, s5
	s_cselect_b32 s6, s7, s6
	s_sub_i32 s7, s6, s5
	s_cmp_ge_u32 s6, s5
	s_cselect_b32 s5, s7, s6
	s_xor_b32 s6, s5, s4
	s_sub_i32 s10, s6, s4
	s_cmpk_gt_i32 s10, 0xbff
	s_cbranch_scc1 .LBB0_30
	v_lshlrev_b32_e32 v6, 3, v120
	v_lshlrev_b32_e32 v1, 4, v120
	v_mov_b32_e32 v3, 0
	v_readlane_b32 s16, v252, 18
	v_and_b32_e32 v6, 56, v6
	s_mul_i32 s7, s3, 0x4100
	v_and_b32_e32 v2, 0xf0, v1
	v_readlane_b32 s26, v252, 28
	v_readlane_b32 s27, v252, 29
	v_mul_u32_u24_e32 v8, 0x104, v6
	v_lshlrev_b32_e32 v6, 1, v6
	v_mov_b32_e32 v7, v3
	v_lshrrev_b32_e32 v0, 4, v120
	v_lshl_add_u64 v[4:5], s[26:27], 0, v[2:3]
	v_lshrrev_b32_e32 v1, 3, v120
	s_movk_i32 s16, 0x104
	v_lshl_add_u64 v[14:15], s[34:35], 0, v[6:7]
	s_mov_b64 s[14:15], 0x2800000
	v_lshl_add_u64 v[12:13], s[66:67], 0, v[2:3]
	v_mov_b32_e32 v2, s7
	s_add_i32 s11, s7, 0
	v_lshl_add_u64 v[6:7], v[14:15], 0, s[14:15]
	v_lshlrev_b32_e32 v9, 2, v1
	s_mov_b64 s[14:15], 0x1800000
	v_mad_u32_u24 v16, v0, s16, v2
	v_and_b32_e32 v2, 15, v120
	v_readlane_b32 s24, v252, 26
	v_readlane_b32 s25, v252, 27
	v_add3_u32 v38, s11, v8, v9
	v_lshl_add_u64 v[8:9], v[14:15], 0, s[14:15]
	s_mov_b64 s[14:15], 0xe00000
	v_lshlrev_b32_e32 v2, 4, v2
	v_readlane_b32 s17, v252, 19
	v_readlane_b32 s18, v252, 20
	v_readlane_b32 s19, v252, 21
	v_readlane_b32 s22, v252, 24
	v_readlane_b32 s23, v252, 25
	s_mov_b64 s[8:9], 0x1000000
	v_lshl_add_u64 v[10:11], v[14:15], 0, s[14:15]
	s_mov_b64 s[14:15], 0x800000
	v_add3_u32 v46, v16, v2, 0
	s_lshl_b32 s7, s6, 2
	s_lshl_b32 s11, s4, 2
	v_lshl_add_u64 v[16:17], s[24:25], 0, v[2:3]
	s_lshl_b32 s6, s6, 6
	s_lshl_b32 s4, s4, 6
	s_mov_b32 s5, 0
	v_lshl_add_u64 v[4:5], v[4:5], 0, s[8:9]
	v_add_u32_e32 v39, 8, v1
	v_or_b32_e32 v40, 16, v1
	v_add_u32_e32 v41, 24, v1
	v_or_b32_e32 v42, 32, v1
	v_add_u32_e32 v43, 40, v1
	v_or_b32_e32 v44, 48, v1
	v_add_u32_e32 v45, 56, v1
	v_lshl_add_u64 v[14:15], v[14:15], 0, s[14:15]
	s_sub_i32 s11, s7, s11
	s_lshl_b32 s14, s33, 5
	v_lshl_add_u64 v[16:17], v[16:17], 0, s[8:9]
	v_add_u32_e32 v47, 0xfffffc1c, v0
	s_sub_i32 s15, s6, s4
	s_lshl_b32 s16, s33, 9
	v_or_b32_e32 v48, 0xfffffc18, v0
	v_add_u32_e32 v49, 0xfffffc14, v0
	v_or_b32_e32 v50, 0xfffffc10, v0
	v_add_u32_e32 v51, 0xfffffc0c, v0
	v_or_b32_e32 v52, 0xfffffc08, v0
	v_add_u32_e32 v53, 0xfffffc04, v0
	v_or_b32_e32 v54, 0xfffffc00, v0
	v_lshl_add_u64 v[18:19], s[22:23], 0, v[2:3]
	v_add_u32_e32 v55, 0xfffff41c, v0
	v_or_b32_e32 v56, 0xfffff418, v0
	v_add_u32_e32 v57, 0xfffff414, v0
	v_or_b32_e32 v58, 0xfffff410, v0
	v_add_u32_e32 v59, 0xfffff40c, v0
	v_or_b32_e32 v60, 0xfffff408, v0
	v_add_u32_e32 v61, 0xfffff404, v0
	v_or_b32_e32 v62, 0xfffff400, v0
	v_lshl_add_u64 v[20:21], s[66:67], 0, v[2:3]
	v_add_u32_e32 v63, 4, v0
	s_movk_i32 s17, 0x7fff
	s_mov_b32 s18, 0xffff0000
	s_movk_i32 s19, 0x3040
	s_mov_b64 s[6:7], 0x60800
	v_mov_b32_e32 v64, 0x3db504f3
	v_mov_b32_e32 v65, 0x3040
	v_readlane_b32 s20, v252, 22
	v_readlane_b32 s21, v252, 23
	v_readlane_b32 s28, v252, 30
	v_readlane_b32 s29, v252, 31
	v_readlane_b32 s30, v252, 32
	v_readlane_b32 s31, v252, 33
	s_branch .LBB0_10

; #define LAS __attribute__((address_space(3)))
;     __device__ __forceinline__ void epi(AccT& acc, const Unit& u, LAS unsigned char* lds, int wr, int wc, int fr, int fq) const {
;     ...
;         if (lane < 32) { const f32x4 p4 = *(const LAS f32x4*)(Pl + row * 4); const float tot = (p4[0] + p4[1]) + (p4[2] + p4[3]);
;             __hip_atomic_store(xbuf + (size_t)(u.pm * 256 + row) * 8 + u.pn, __builtin_bit_cast(unsigned, tot), __ATOMIC_RELAXED, __HIP_MEMORY_SCOPE_AGENT); }
;         asm volatile("s_waitcnt vmcnt(0)" ::: "memory");
;         if (lane == 0) __hip_atomic_fetch_add(cnt + 64 * u.pm, 1u, __ATOMIC_RELAXED, __HIP_MEMORY_SCOPE_AGENT);
;         if (wid == 0) {
;             bool dead = false; const unsigned long long t0 = __builtin_amdgcn_s_memrealtime();
;             for (;;) {
;                 if ((unsigned)__builtin_amdgcn_readfirstlane(__hip_atomic_load(cnt + 64 * u.pm, __ATOMIC_RELAXED, __HIP_MEMORY_SCOPE_AGENT)) >= 64u) break;
;                 if (__builtin_amdgcn_s_memrealtime() - t0 > 2000000ull) { if (lane == 0) __hip_atomic_store(tmo, 1u, __ATOMIC_RELAXED, __HIP_MEMORY_SCOPE_AGENT); dead = true; break; }
;                 __builtin_amdgcn_s_sleep(2);
;             }
;             __builtin_amdgcn_fence(__ATOMIC_ACQUIRE, "agent");
;             if (lane == 0) flag[0] = dead ? 1u : 0u;
;         }
;         asm volatile("s_waitcnt vmcnt(0) lgkmcnt(0)" ::: "memory"); __builtin_amdgcn_s_barrier(); asm volatile("" ::: "memory");
;         const bool bad = flag[0] != 0u;
;         if (lane < 32) { const unsigned* sp = xbuf + (size_t)(u.pm * 256 + row) * 8; float tot = 0.f;
; #pragma unroll
;             for (int t = 0; t < 8; ++t) tot += __builtin_bit_cast(float, __hip_atomic_load(sp + t, __ATOMIC_RELAXED, __HIP_MEMORY_SCOPE_AGENT));
;             Sl[row] = 1.0f / sqrtf(tot * (1.f / D) + EPS); }
.LBB0_438:
	s_or_b64 exec, exec, s[62:63]
	v_mov_b32_e32 v52, 0
	s_and_saveexec_b64 s[62:63], s[6:7]
	s_cbranch_execz .LBB0_460
	v_lshlrev_b64 v[0:1], 5, v[0:1]
	v_lshl_add_u64 v[0:1], s[46:47], 0, v[0:1]
	s_mov_b32 s12, 0
.Lxpoll5_poll:
	global_load_dwordx4 v[2:5], v[0:1], off sc1
	global_load_dwordx4 v[6:9], v[0:1], off offset:16 sc1
	s_waitcnt vmcnt(0)
	v_min_u32_e32 v10, v2, v3
	v_min_u32_e32 v11, v4, v5
	v_min_u32_e32 v10, v10, v11
	v_min_u32_e32 v11, v6, v7
	v_min_u32_e32 v10, v10, v11
	v_min_u32_e32 v11, v8, v9
	v_min_u32_e32 v10, v10, v11
	v_cmp_ne_u32_e32 vcc, 0, v10
	s_cmp_eq_u64 vcc, exec
	s_cbranch_scc1 .Lxpoll5_ready
	s_add_i32 s12, s12, 1
	s_cmp_lt_u32 s12, 0x1000
	s_cbranch_scc1 .Lxpoll5_poll
.Lxpoll5_ready:
	s_mov_b32 s12, 0xf800000
	v_add_f32_e32 v1, 0, v2
	v_add_f32_e32 v1, v1, v3
	v_add_f32_e32 v1, v1, v4
	v_add_f32_e32 v1, v1, v5
	v_add_f32_e32 v1, v1, v6
	v_add_f32_e32 v1, v1, v7
	v_add_f32_e32 v1, v1, v8
	v_add_f32_e32 v0, v1, v9
	v_fmamk_f32 v0, v0, 0x3a800000, v239
	v_mul_f32_e32 v1, 0x4f800000, v0
	v_cmp_gt_f32_e32 vcc, s12, v0
	s_nop 1
	v_cndmask_b32_e32 v0, v0, v1, vcc
	v_sqrt_f32_e32 v1, v0
	s_nop 0
	v_add_u32_e32 v2, -1, v1
	v_add_u32_e32 v3, 1, v1
	v_fma_f32 v4, -v2, v1, v0
	v_fma_f32 v5, -v3, v1, v0
	v_cmp_ge_f32_e64 s[12:13], 0, v4
	s_nop 1
	v_cndmask_b32_e64 v1, v1, v2, s[12:13]
	v_cmp_lt_f32_e64 s[12:13], 0, v5
	s_nop 1
	v_cndmask_b32_e64 v1, v1, v3, s[12:13]
	v_mul_f32_e32 v2, 0x37800000, v1
	v_cndmask_b32_e32 v1, v1, v2, vcc
	v_cmp_class_f32_e32 vcc, v0, v240
	s_nop 1
	v_cndmask_b32_e32 v0, v1, v0, vcc
	v_div_scale_f32 v1, s[12:13], v0, v0, 1.0
	v_rcp_f32_e32 v2, v1
	v_div_scale_f32 v3, vcc, 1.0, v0, 1.0
	v_fma_f32 v4, -v1, v2, 1.0
	v_fmac_f32_e32 v2, v4, v2
	v_mul_f32_e32 v4, v3, v2
	v_fma_f32 v5, -v1, v4, v3
	v_fmac_f32_e32 v4, v5, v2
	v_fma_f32 v1, -v1, v4, v3
	v_div_fmas_f32 v1, v1, v2, v4
	v_div_fixup_f32 v0, v1, v0, 1.0
	ds_write_b32 v217, v0

; #define LAS __attribute__((address_space(3)))
; #define ESTAMP(i) do { if (PROBE_K >= 100 && MODE == 1 && blockIdx.x == 0 && wr * 4 + wc == 0 && fr + 16 * fq == 0 && tmo != nullptr) { ((unsigned long long*)tmo)[25600 + 64 + (i)] = __builtin_amdgcn_s_memrealtime(); } } while (0)
;     __device__ __forceinline__ void epi(AccT& acc, const Unit& u, LAS unsigned char* lds, int wr, int wc, int fr, int fq) const {
;     ...
;         if (lane < 32) { const f32x4 p4 = *(const LAS f32x4*)(Pl + row * 4); const float tot = (p4[0] + p4[1]) + (p4[2] + p4[3]);
;             __hip_atomic_store(xbuf + (size_t)(u.pm * 256 + row) * 4 + u.pn, __builtin_bit_cast(unsigned, tot), __ATOMIC_RELAXED, __HIP_MEMORY_SCOPE_AGENT); }
;         asm volatile("s_waitcnt vmcnt(0)" ::: "memory");
;         if (lane == 0) __hip_atomic_fetch_add(cnt + 64 * u.pm, 1u, __ATOMIC_RELAXED, __HIP_MEMORY_SCOPE_AGENT);
;         ESTAMP(2);
;         if (wid == 0) {
;             bool dead = false; const unsigned long long t0 = __builtin_amdgcn_s_memrealtime();
;             for (;;) {
;                 if ((unsigned)__builtin_amdgcn_readfirstlane(__hip_atomic_load(cnt + 64 * u.pm, __ATOMIC_RELAXED, __HIP_MEMORY_SCOPE_AGENT)) >= 32u) break;
;                 if (__builtin_amdgcn_s_memrealtime() - t0 > 2000000ull) { if (lane == 0) __hip_atomic_store(tmo, 1u, __ATOMIC_RELAXED, __HIP_MEMORY_SCOPE_AGENT); dead = true; break; }
;                 __builtin_amdgcn_s_sleep(2);
;             }
;             __builtin_amdgcn_fence(__ATOMIC_ACQUIRE, "agent");
;             if (lane == 0) flag[0] = dead ? 1u : 0u;
;         }
;         asm volatile("s_waitcnt vmcnt(0) lgkmcnt(0)" ::: "memory"); __builtin_amdgcn_s_barrier(); asm volatile("" ::: "memory");
;         const bool bad = flag[0] != 0u;
;         ESTAMP(3);
;         if (lane < 32) { const unsigned* sp = xbuf + (size_t)(u.pm * 256 + row) * 4; float tot = 0.f;
; #pragma unroll
;             for (int t = 0; t < 4; ++t) tot += __builtin_bit_cast(float, __hip_atomic_load(sp + t, __ATOMIC_RELAXED, __HIP_MEMORY_SCOPE_AGENT));
;             Sl[row] = 1.0f / sqrtf(tot * (1.f / D) + EPS); }
.LBB0_658:
	s_or_b64 exec, exec, s[88:89]
	v_mov_b32_e32 v66, 0
	s_and_saveexec_b64 s[82:83], s[10:11]
	s_cbranch_execz .LBB0_681
	v_lshl_add_u64 v[64:65], v[64:65], 4, s[64:65]
	s_mov_b32 s22, 0
.Lxp20_poll:
	global_load_dwordx4 v[224:227], v[64:65], off sc1
	s_waitcnt vmcnt(0)
	v_min_u32_e32 v228, v224, v225
	v_min_u32_e32 v229, v226, v227
	v_min_u32_e32 v228, v228, v229
	v_cmp_ne_u32_e32 vcc, 0, v228
	s_cmp_eq_u64 vcc, exec
	s_cbranch_scc1 .Lxp20_ready
	s_add_i32 s22, s22, 1
	s_cmp_lt_u32 s22, 0x1000
	s_cbranch_scc1 .Lxp20_poll
.Lxp20_ready:
	s_mov_b32 s22, 0xf800000
	v_add_f32_e32 v65, 0, v224
	v_add_f32_e32 v65, v65, v225
	v_add_f32_e32 v65, v65, v226
	v_add_f32_e32 v64, v65, v227
	v_fmamk_f32 v64, v64, 0x3a800000, v220
	v_mul_f32_e32 v65, 0x4f800000, v64
	v_cmp_gt_f32_e32 vcc, s22, v64
	s_nop 1
	v_cndmask_b32_e32 v64, v64, v65, vcc
	v_sqrt_f32_e32 v65, v64
	s_nop 0
	v_add_u32_e32 v67, -1, v65
	v_add_u32_e32 v68, 1, v65
	v_fma_f32 v69, -v67, v65, v64
	v_fma_f32 v70, -v68, v65, v64
	v_cmp_ge_f32_e64 s[22:23], 0, v69
	s_nop 1
	v_cndmask_b32_e64 v65, v65, v67, s[22:23]
	v_cmp_lt_f32_e64 s[22:23], 0, v70
	s_nop 1
	v_cndmask_b32_e64 v65, v65, v68, s[22:23]
	v_mul_f32_e32 v67, 0x37800000, v65
	v_cndmask_b32_e32 v65, v65, v67, vcc
	v_cmp_class_f32_e32 vcc, v64, v221
	s_nop 1
	v_cndmask_b32_e32 v64, v65, v64, vcc
	v_div_scale_f32 v65, s[22:23], v64, v64, 1.0
	v_rcp_f32_e32 v67, v65
	v_div_scale_f32 v68, vcc, 1.0, v64, 1.0
	v_fma_f32 v69, -v65, v67, 1.0
	v_fmac_f32_e32 v67, v69, v67
	v_mul_f32_e32 v69, v68, v67
	v_fma_f32 v70, -v65, v69, v68
	v_fmac_f32_e32 v69, v70, v67
	v_fma_f32 v65, -v65, v69, v68
	v_div_fmas_f32 v65, v65, v67, v69
	v_div_fixup_f32 v64, v65, v64, 1.0
	ds_write_b32 v204, v64

; #define LAS __attribute__((address_space(3)))
; #define ESTAMP(i) do { if (PROBE_K >= 100 && MODE == 1 && blockIdx.x == 0 && wr * 4 + wc == 0 && fr + 16 * fq == 0 && tmo != nullptr) { ((unsigned long long*)tmo)[25600 + 64 + (i)] = __builtin_amdgcn_s_memrealtime(); } } while (0)
;     __device__ __forceinline__ void epi(AccT& acc, const Unit& u, LAS unsigned char* lds, int wr, int wc, int fr, int fq) const {
;     ...
;         if (lane < 32) { const f32x4 p4 = *(const LAS f32x4*)(Pl + row * 4); const float tot = (p4[0] + p4[1]) + (p4[2] + p4[3]);
;             __hip_atomic_store(xbuf + (size_t)(u.pm * 256 + row) * 4 + u.pn, __builtin_bit_cast(unsigned, tot), __ATOMIC_RELAXED, __HIP_MEMORY_SCOPE_AGENT); }
;         asm volatile("s_waitcnt vmcnt(0)" ::: "memory");
;         if (lane == 0) __hip_atomic_fetch_add(cnt + 64 * u.pm, 1u, __ATOMIC_RELAXED, __HIP_MEMORY_SCOPE_AGENT);
;         ESTAMP(2);
;         if (wid == 0) {
;             bool dead = false; const unsigned long long t0 = __builtin_amdgcn_s_memrealtime();
;             for (;;) {
;                 if ((unsigned)__builtin_amdgcn_readfirstlane(__hip_atomic_load(cnt + 64 * u.pm, __ATOMIC_RELAXED, __HIP_MEMORY_SCOPE_AGENT)) >= 32u) break;
;                 if (__builtin_amdgcn_s_memrealtime() - t0 > 2000000ull) { if (lane == 0) __hip_atomic_store(tmo, 1u, __ATOMIC_RELAXED, __HIP_MEMORY_SCOPE_AGENT); dead = true; break; }
;                 __builtin_amdgcn_s_sleep(2);
;             }
;             __builtin_amdgcn_fence(__ATOMIC_ACQUIRE, "agent");
;             if (lane == 0) flag[0] = dead ? 1u : 0u;
;         }
;         asm volatile("s_waitcnt vmcnt(0) lgkmcnt(0)" ::: "memory"); __builtin_amdgcn_s_barrier(); asm volatile("" ::: "memory");
;         const bool bad = flag[0] != 0u;
;         ESTAMP(3);
;         if (lane < 32) { const unsigned* sp = xbuf + (size_t)(u.pm * 256 + row) * 4; float tot = 0.f;
; #pragma unroll
;             for (int t = 0; t < 4; ++t) tot += __builtin_bit_cast(float, __hip_atomic_load(sp + t, __ATOMIC_RELAXED, __HIP_MEMORY_SCOPE_AGENT));
;             Sl[row] = 1.0f / sqrtf(tot * (1.f / D) + EPS); }
.LBB0_1019:
	s_or_b64 exec, exec, s[24:25]
	v_mov_b32_e32 v66, 0
	s_and_saveexec_b64 s[74:75], s[12:13]
	s_cbranch_execz .LBB0_1041
	v_lshl_add_u64 v[64:65], v[64:65], 4, s[30:31]
	s_mov_b32 s24, 0
.Lxpoll21_poll:
	global_load_dwordx4 v[228:231], v[64:65], off sc1
	s_waitcnt vmcnt(0)
	v_min_u32_e32 v232, v228, v229
	v_min_u32_e32 v233, v230, v231
	v_min_u32_e32 v232, v232, v233
	v_cmp_ne_u32_e32 vcc, 0, v232
	s_cmp_eq_u64 vcc, exec
	s_cbranch_scc1 .Lxpoll21_ready
	s_add_i32 s24, s24, 1
	s_cmp_lt_u32 s24, 0x1000
	s_cbranch_scc1 .Lxpoll21_poll
.Lxpoll21_ready:
	s_mov_b32 s24, 0xf800000
	v_add_f32_e32 v65, 0, v228
	v_add_f32_e32 v65, v65, v229
	v_add_f32_e32 v65, v65, v230
	v_add_f32_e32 v64, v65, v231
	v_fmamk_f32 v64, v64, 0x3a800000, v220
	v_mul_f32_e32 v65, 0x4f800000, v64
	v_cmp_gt_f32_e32 vcc, s24, v64
	s_nop 1
	v_cndmask_b32_e32 v64, v64, v65, vcc
	v_sqrt_f32_e32 v65, v64
	s_nop 0
	v_add_u32_e32 v67, -1, v65
	v_add_u32_e32 v68, 1, v65
	v_fma_f32 v69, -v67, v65, v64
	v_fma_f32 v70, -v68, v65, v64
	v_cmp_ge_f32_e64 s[24:25], 0, v69
	s_nop 1
	v_cndmask_b32_e64 v65, v65, v67, s[24:25]
	v_cmp_lt_f32_e64 s[24:25], 0, v70
	s_nop 1
	v_cndmask_b32_e64 v65, v65, v68, s[24:25]
	v_mul_f32_e32 v67, 0x37800000, v65
	v_cndmask_b32_e32 v65, v65, v67, vcc
	v_cmp_class_f32_e32 vcc, v64, v221
	s_nop 1
	v_cndmask_b32_e32 v64, v65, v64, vcc
	v_div_scale_f32 v65, s[24:25], v64, v64, 1.0
	v_rcp_f32_e32 v67, v65
	v_div_scale_f32 v68, vcc, 1.0, v64, 1.0
	v_fma_f32 v69, -v65, v67, 1.0
	v_fmac_f32_e32 v67, v69, v67
	v_mul_f32_e32 v69, v68, v67
	v_fma_f32 v70, -v65, v69, v68
	v_fmac_f32_e32 v69, v70, v67
	v_fma_f32 v65, -v65, v69, v68
	v_div_fmas_f32 v65, v65, v67, v69
	v_div_fixup_f32 v64, v65, v64, 1.0
	ds_write_b32 v204, v64

; #define LAS __attribute__((address_space(3)))
; #define ESTAMP(i) do { if (PROBE_K >= 100 && MODE == 1 && blockIdx.x == 0 && wr * 4 + wc == 0 && fr + 16 * fq == 0 && tmo != nullptr) { ((unsigned long long*)tmo)[25600 + 64 + (i)] = __builtin_amdgcn_s_memrealtime(); } } while (0)
;     __device__ __forceinline__ void epi(AccT& acc, const Unit& u, LAS unsigned char* lds, int wr, int wc, int fr, int fq) const {
;     ...
;         if (lane < 32) { const f32x4 p4 = *(const LAS f32x4*)(Pl + row * 4); const float tot = (p4[0] + p4[1]) + (p4[2] + p4[3]);
;             __hip_atomic_store(xbuf + (size_t)(u.pm * 256 + row) * 4 + u.pn, __builtin_bit_cast(unsigned, tot), __ATOMIC_RELAXED, __HIP_MEMORY_SCOPE_AGENT); }
;         asm volatile("s_waitcnt vmcnt(0)" ::: "memory");
;         if (lane == 0) __hip_atomic_fetch_add(cnt + 64 * u.pm, 1u, __ATOMIC_RELAXED, __HIP_MEMORY_SCOPE_AGENT);
;         ESTAMP(2);
;         if (wid == 0) {
;             bool dead = false; const unsigned long long t0 = __builtin_amdgcn_s_memrealtime();
;             for (;;) {
;                 if ((unsigned)__builtin_amdgcn_readfirstlane(__hip_atomic_load(cnt + 64 * u.pm, __ATOMIC_RELAXED, __HIP_MEMORY_SCOPE_AGENT)) >= 32u) break;
;                 if (__builtin_amdgcn_s_memrealtime() - t0 > 2000000ull) { if (lane == 0) __hip_atomic_store(tmo, 1u, __ATOMIC_RELAXED, __HIP_MEMORY_SCOPE_AGENT); dead = true; break; }
;                 __builtin_amdgcn_s_sleep(2);
;             }
;             __builtin_amdgcn_fence(__ATOMIC_ACQUIRE, "agent");
;             if (lane == 0) flag[0] = dead ? 1u : 0u;
;         }
;         asm volatile("s_waitcnt vmcnt(0) lgkmcnt(0)" ::: "memory"); __builtin_amdgcn_s_barrier(); asm volatile("" ::: "memory");
;         const bool bad = flag[0] != 0u;
;         ESTAMP(3);
;         if (lane < 32) { const unsigned* sp = xbuf + (size_t)(u.pm * 256 + row) * 4; float tot = 0.f;
; #pragma unroll
;             for (int t = 0; t < 4; ++t) tot += __builtin_bit_cast(float, __hip_atomic_load(sp + t, __ATOMIC_RELAXED, __HIP_MEMORY_SCOPE_AGENT));
;             Sl[row] = 1.0f / sqrtf(tot * (1.f / D) + EPS); }
.LBB0_1241:
	s_or_b64 exec, exec, s[56:57]
	v_mov_b32_e32 v64, 0
	s_and_saveexec_b64 s[14:15], s[16:17]
	s_cbranch_execz .LBB0_1263
	v_lshl_add_u64 v[0:1], v[0:1], 4, s[26:27]
	s_mov_b32 s12, 0
.Lxpoll19_poll:
	global_load_dwordx4 v[228:231], v[0:1], off sc1
	s_waitcnt vmcnt(0)
	v_min_u32_e32 v232, v228, v229
	v_min_u32_e32 v233, v230, v231
	v_min_u32_e32 v232, v232, v233
	v_cmp_ne_u32_e32 vcc, 0, v232
	s_cmp_eq_u64 vcc, exec
	s_cbranch_scc1 .Lxpoll19_ready
	s_add_i32 s12, s12, 1
	s_cmp_lt_u32 s12, 0x1000
	s_cbranch_scc1 .Lxpoll19_poll
.Lxpoll19_ready:
	s_mov_b32 s12, 0xf800000
	v_add_f32_e32 v1, 0, v228
	v_add_f32_e32 v1, v1, v229
	v_add_f32_e32 v1, v1, v230
	v_add_f32_e32 v0, v1, v231
	v_fmamk_f32 v0, v0, 0x3a800000, v209
	v_mul_f32_e32 v1, 0x4f800000, v0
	v_cmp_gt_f32_e32 vcc, s12, v0
	s_nop 1
	v_cndmask_b32_e32 v0, v0, v1, vcc
	v_sqrt_f32_e32 v1, v0
	s_nop 0
	v_add_u32_e32 v2, -1, v1
	v_add_u32_e32 v3, 1, v1
	v_fma_f32 v4, -v2, v1, v0
	v_fma_f32 v5, -v3, v1, v0
	v_cmp_ge_f32_e64 s[12:13], 0, v4
	s_nop 1
	v_cndmask_b32_e64 v1, v1, v2, s[12:13]
	v_cmp_lt_f32_e64 s[12:13], 0, v5
	s_nop 1
	v_cndmask_b32_e64 v1, v1, v3, s[12:13]
	v_mul_f32_e32 v2, 0x37800000, v1
	v_cndmask_b32_e32 v1, v1, v2, vcc
	v_cmp_class_f32_e32 vcc, v0, v210
	s_nop 1
	v_cndmask_b32_e32 v0, v1, v0, vcc
	v_div_scale_f32 v1, s[12:13], v0, v0, 1.0
	v_rcp_f32_e32 v2, v1
	v_div_scale_f32 v3, vcc, 1.0, v0, 1.0
	v_fma_f32 v4, -v1, v2, 1.0
	v_fmac_f32_e32 v2, v4, v2
	v_mul_f32_e32 v4, v3, v2
	v_fma_f32 v5, -v1, v4, v3
	v_fmac_f32_e32 v4, v5, v2
	v_fma_f32 v1, -v1, v4, v3
	v_div_fmas_f32 v1, v1, v2, v4
	v_div_fixup_f32 v0, v1, v0, 1.0
	ds_write_b32 v197, v0
